# NSA top-16 selection: per-row rank loops (serial LDS round trips) replaced by one batched row read + unrolled register compares
# baseline (speedup 1.0000x reference)
; DI void nsa_unit(const Params& p, lds8* lds, int bl, int g, int qb32) {
;     ...
;   { const int qq = tid >> 4, sb2 = (tid & 15) * 2; unsigned bits = 0u;
; #pragma unroll
;     for (int e = 0; e < 2; ++e) { const int s = sb2 + e;
;       if (s <= blk) { const float v = score[qq * 33 + s]; int rank = 0;
;         for (int s2 = 0; s2 <= blk; ++s2) { const float v2 = score[qq * 33 + s2]; rank += (v2 > v || (v2 == v && s2 < s)) ? 1 : 0; }
;         if (rank < 16) bits |= 1u << s; } }
.LBB0_908:
	s_movk_i32 s1, 0x84
	s_or_b64 exec, exec, s[10:11]
	v_ashrrev_i32_e32 v55, 4, v136
	v_and_b32_e32 v56, 15, v136
	v_mul_lo_u32 v57, v55, s1
	v_readlane_b32 s1, v255, 11
	v_lshlrev_b32_e32 v48, 1, v56
	v_lshlrev_b32_e32 v54, 3, v54
	v_add_u32_e32 v58, s1, v57
	v_cmp_ge_u32_e32 vcc, s77, v48
	v_mov_b32_e32 v60, 0
	v_lshl_add_u32 v59, v48, 2, v58
	s_waitcnt lgkmcnt(0)
	s_barrier
	ds_read2_b32 v[176:177], v59 offset1:1
	ds_read2_b32 v[160:161], v58 offset0:0 offset1:1
	ds_read2_b32 v[162:163], v58 offset0:2 offset1:3
	ds_read2_b32 v[164:165], v58 offset0:4 offset1:5
	ds_read2_b32 v[166:167], v58 offset0:6 offset1:7
	ds_read2_b32 v[168:169], v58 offset0:8 offset1:9
	ds_read2_b32 v[170:171], v58 offset0:10 offset1:11
	ds_read2_b32 v[172:173], v58 offset0:12 offset1:13
	ds_read2_b32 v[174:175], v58 offset0:14 offset1:15
	v_mov_b32_e32 v178, 0
	v_mov_b32_e32 v179, 0
	s_waitcnt lgkmcnt(0)
	s_cmp_lt_u32 s77, 16
	s_cbranch_scc1 .Lrk_lo
	ds_read2_b32 v[142:143], v58 offset0:16 offset1:17
	ds_read2_b32 v[144:145], v58 offset0:18 offset1:19
	ds_read2_b32 v[146:147], v58 offset0:20 offset1:21
	ds_read2_b32 v[148:149], v58 offset0:22 offset1:23
	ds_read2_b32 v[150:151], v58 offset0:24 offset1:25
	ds_read2_b32 v[152:153], v58 offset0:26 offset1:27
	ds_read2_b32 v[154:155], v58 offset0:28 offset1:29
	ds_read2_b32 v[156:157], v58 offset0:30 offset1:31
.Lrk_lo:
	v_cmp_lt_u32_e64 s[10:11], 0, v48
	v_cmp_eq_f32_e64 s[8:9], v160, v176
	v_cmp_gt_f32_e32 vcc, v160, v176
	s_and_b64 s[8:9], s[8:9], s[10:11]
	s_or_b64 vcc, vcc, s[8:9]
	v_cmp_le_u32_e64 s[12:13], 0, v48
	v_addc_co_u32_e32 v178, vcc, 0, v178, vcc
	v_cmp_eq_f32_e64 s[8:9], v160, v177
	v_cmp_gt_f32_e32 vcc, v160, v177
	s_and_b64 s[8:9], s[8:9], s[12:13]
	s_or_b64 vcc, vcc, s[8:9]
	v_lshlrev_b32_e64 v50, v48, 1
	v_addc_co_u32_e32 v179, vcc, 0, v179, vcc
	s_cmp_lt_u32 s77, 1
	s_cbranch_scc1 .Lrk_done
	v_cmp_lt_u32_e64 s[10:11], 1, v48
	v_cmp_eq_f32_e64 s[8:9], v161, v176
	v_cmp_gt_f32_e32 vcc, v161, v176
	s_and_b64 s[8:9], s[8:9], s[10:11]
	s_or_b64 vcc, vcc, s[8:9]
	v_cmp_le_u32_e64 s[12:13], 1, v48
	v_addc_co_u32_e32 v178, vcc, 0, v178, vcc
	v_cmp_eq_f32_e64 s[8:9], v161, v177
	v_cmp_gt_f32_e32 vcc, v161, v177
	s_and_b64 s[8:9], s[8:9], s[12:13]
	s_or_b64 vcc, vcc, s[8:9]
	v_lshlrev_b32_e64 v50, v48, 1
	v_addc_co_u32_e32 v179, vcc, 0, v179, vcc
	s_cmp_lt_u32 s77, 2
	s_cbranch_scc1 .Lrk_done
	v_cmp_lt_u32_e64 s[10:11], 2, v48
	v_cmp_eq_f32_e64 s[8:9], v162, v176
	v_cmp_gt_f32_e32 vcc, v162, v176
	s_and_b64 s[8:9], s[8:9], s[10:11]
	s_or_b64 vcc, vcc, s[8:9]
	v_cmp_le_u32_e64 s[12:13], 2, v48
	v_addc_co_u32_e32 v178, vcc, 0, v178, vcc
	v_cmp_eq_f32_e64 s[8:9], v162, v177
	v_cmp_gt_f32_e32 vcc, v162, v177
	s_and_b64 s[8:9], s[8:9], s[12:13]
	s_or_b64 vcc, vcc, s[8:9]
	v_lshlrev_b32_e64 v50, v48, 1
	v_addc_co_u32_e32 v179, vcc, 0, v179, vcc
	s_cmp_lt_u32 s77, 3
	s_cbranch_scc1 .Lrk_done
	v_cmp_lt_u32_e64 s[10:11], 3, v48
	v_cmp_eq_f32_e64 s[8:9], v163, v176
	v_cmp_gt_f32_e32 vcc, v163, v176
	s_and_b64 s[8:9], s[8:9], s[10:11]
	s_or_b64 vcc, vcc, s[8:9]
	v_cmp_le_u32_e64 s[12:13], 3, v48
	v_addc_co_u32_e32 v178, vcc, 0, v178, vcc
	v_cmp_eq_f32_e64 s[8:9], v163, v177
	v_cmp_gt_f32_e32 vcc, v163, v177
	s_and_b64 s[8:9], s[8:9], s[12:13]
	s_or_b64 vcc, vcc, s[8:9]
	v_lshlrev_b32_e64 v50, v48, 1
	v_addc_co_u32_e32 v179, vcc, 0, v179, vcc
	s_cmp_lt_u32 s77, 4
	s_cbranch_scc1 .Lrk_done
	v_cmp_lt_u32_e64 s[10:11], 4, v48
	v_cmp_eq_f32_e64 s[8:9], v164, v176
	v_cmp_gt_f32_e32 vcc, v164, v176
	s_and_b64 s[8:9], s[8:9], s[10:11]
	s_or_b64 vcc, vcc, s[8:9]
	v_cmp_le_u32_e64 s[12:13], 4, v48
	v_addc_co_u32_e32 v178, vcc, 0, v178, vcc
	v_cmp_eq_f32_e64 s[8:9], v164, v177
	v_cmp_gt_f32_e32 vcc, v164, v177
	s_and_b64 s[8:9], s[8:9], s[12:13]
	s_or_b64 vcc, vcc, s[8:9]
	v_lshlrev_b32_e64 v50, v48, 1
	v_addc_co_u32_e32 v179, vcc, 0, v179, vcc
	s_cmp_lt_u32 s77, 5
	s_cbranch_scc1 .Lrk_done
	v_cmp_lt_u32_e64 s[10:11], 5, v48
	v_cmp_eq_f32_e64 s[8:9], v165, v176
	v_cmp_gt_f32_e32 vcc, v165, v176
	s_and_b64 s[8:9], s[8:9], s[10:11]
	s_or_b64 vcc, vcc, s[8:9]
	v_cmp_le_u32_e64 s[12:13], 5, v48
	v_addc_co_u32_e32 v178, vcc, 0, v178, vcc
	v_cmp_eq_f32_e64 s[8:9], v165, v177
	v_cmp_gt_f32_e32 vcc, v165, v177
	s_and_b64 s[8:9], s[8:9], s[12:13]
	s_or_b64 vcc, vcc, s[8:9]
	v_lshlrev_b32_e64 v50, v48, 1
	v_addc_co_u32_e32 v179, vcc, 0, v179, vcc
	s_cmp_lt_u32 s77, 6
	s_cbranch_scc1 .Lrk_done
	v_cmp_lt_u32_e64 s[10:11], 6, v48
	v_cmp_eq_f32_e64 s[8:9], v166, v176
	v_cmp_gt_f32_e32 vcc, v166, v176
	s_and_b64 s[8:9], s[8:9], s[10:11]
	s_or_b64 vcc, vcc, s[8:9]
	v_cmp_le_u32_e64 s[12:13], 6, v48
	v_addc_co_u32_e32 v178, vcc, 0, v178, vcc
	v_cmp_eq_f32_e64 s[8:9], v166, v177
	v_cmp_gt_f32_e32 vcc, v166, v177
	s_and_b64 s[8:9], s[8:9], s[12:13]
	s_or_b64 vcc, vcc, s[8:9]
	v_lshlrev_b32_e64 v50, v48, 1
	v_addc_co_u32_e32 v179, vcc, 0, v179, vcc
	s_cmp_lt_u32 s77, 7
	s_cbranch_scc1 .Lrk_done
	v_cmp_lt_u32_e64 s[10:11], 7, v48
	v_cmp_eq_f32_e64 s[8:9], v167, v176
	v_cmp_gt_f32_e32 vcc, v167, v176
	s_and_b64 s[8:9], s[8:9], s[10:11]
	s_or_b64 vcc, vcc, s[8:9]
	v_cmp_le_u32_e64 s[12:13], 7, v48
	v_addc_co_u32_e32 v178, vcc, 0, v178, vcc
	v_cmp_eq_f32_e64 s[8:9], v167, v177
	v_cmp_gt_f32_e32 vcc, v167, v177
	s_and_b64 s[8:9], s[8:9], s[12:13]
	s_or_b64 vcc, vcc, s[8:9]
	v_lshlrev_b32_e64 v50, v48, 1
	v_addc_co_u32_e32 v179, vcc, 0, v179, vcc
	s_cmp_lt_u32 s77, 8
	s_cbranch_scc1 .Lrk_done
; DI void nsa_unit(const Params& p, lds8* lds, int bl, int g, int qb32) {
;     ...
;       if (s <= blk) { const float v = score[qq * 33 + s]; int rank = 0;
;         for (int s2 = 0; s2 <= blk; ++s2) { const float v2 = score[qq * 33 + s2]; rank += (v2 > v || (v2 == v && s2 < s)) ? 1 : 0; }
;         if (rank < 16) bits |= 1u << s; } }
	v_cmp_lt_u32_e64 s[10:11], 8, v48
	v_cmp_eq_f32_e64 s[8:9], v168, v176
	v_cmp_gt_f32_e32 vcc, v168, v176
	s_and_b64 s[8:9], s[8:9], s[10:11]
	s_or_b64 vcc, vcc, s[8:9]
	v_cmp_le_u32_e64 s[12:13], 8, v48
	v_addc_co_u32_e32 v178, vcc, 0, v178, vcc
	v_cmp_eq_f32_e64 s[8:9], v168, v177
	v_cmp_gt_f32_e32 vcc, v168, v177
	s_and_b64 s[8:9], s[8:9], s[12:13]
	s_or_b64 vcc, vcc, s[8:9]
	v_lshlrev_b32_e64 v50, v48, 1
	v_addc_co_u32_e32 v179, vcc, 0, v179, vcc
	s_cmp_lt_u32 s77, 9
	s_cbranch_scc1 .Lrk_done
	v_cmp_lt_u32_e64 s[10:11], 9, v48
	v_cmp_eq_f32_e64 s[8:9], v169, v176
	v_cmp_gt_f32_e32 vcc, v169, v176
	s_and_b64 s[8:9], s[8:9], s[10:11]
	s_or_b64 vcc, vcc, s[8:9]
	v_cmp_le_u32_e64 s[12:13], 9, v48
	v_addc_co_u32_e32 v178, vcc, 0, v178, vcc
	v_cmp_eq_f32_e64 s[8:9], v169, v177
	v_cmp_gt_f32_e32 vcc, v169, v177
	s_and_b64 s[8:9], s[8:9], s[12:13]
	s_or_b64 vcc, vcc, s[8:9]
	v_lshlrev_b32_e64 v50, v48, 1
	v_addc_co_u32_e32 v179, vcc, 0, v179, vcc
	s_cmp_lt_u32 s77, 10
	s_cbranch_scc1 .Lrk_done
	v_cmp_lt_u32_e64 s[10:11], 10, v48
	v_cmp_eq_f32_e64 s[8:9], v170, v176
	v_cmp_gt_f32_e32 vcc, v170, v176
	s_and_b64 s[8:9], s[8:9], s[10:11]
	s_or_b64 vcc, vcc, s[8:9]
	v_cmp_le_u32_e64 s[12:13], 10, v48
	v_addc_co_u32_e32 v178, vcc, 0, v178, vcc
	v_cmp_eq_f32_e64 s[8:9], v170, v177
	v_cmp_gt_f32_e32 vcc, v170, v177
	s_and_b64 s[8:9], s[8:9], s[12:13]
	s_or_b64 vcc, vcc, s[8:9]
	v_lshlrev_b32_e64 v50, v48, 1
	v_addc_co_u32_e32 v179, vcc, 0, v179, vcc
	s_cmp_lt_u32 s77, 11
	s_cbranch_scc1 .Lrk_done
	v_cmp_lt_u32_e64 s[10:11], 11, v48
	v_cmp_eq_f32_e64 s[8:9], v171, v176
	v_cmp_gt_f32_e32 vcc, v171, v176
	s_and_b64 s[8:9], s[8:9], s[10:11]
	s_or_b64 vcc, vcc, s[8:9]
	v_cmp_le_u32_e64 s[12:13], 11, v48
	v_addc_co_u32_e32 v178, vcc, 0, v178, vcc
	v_cmp_eq_f32_e64 s[8:9], v171, v177
	v_cmp_gt_f32_e32 vcc, v171, v177
	s_and_b64 s[8:9], s[8:9], s[12:13]
	s_or_b64 vcc, vcc, s[8:9]
	v_lshlrev_b32_e64 v50, v48, 1
	v_addc_co_u32_e32 v179, vcc, 0, v179, vcc
	s_cmp_lt_u32 s77, 12
	s_cbranch_scc1 .Lrk_done
	v_cmp_lt_u32_e64 s[10:11], 12, v48
	v_cmp_eq_f32_e64 s[8:9], v172, v176
	v_cmp_gt_f32_e32 vcc, v172, v176
	s_and_b64 s[8:9], s[8:9], s[10:11]
	s_or_b64 vcc, vcc, s[8:9]
	v_cmp_le_u32_e64 s[12:13], 12, v48
	v_addc_co_u32_e32 v178, vcc, 0, v178, vcc
	v_cmp_eq_f32_e64 s[8:9], v172, v177
	v_cmp_gt_f32_e32 vcc, v172, v177
	s_and_b64 s[8:9], s[8:9], s[12:13]
	s_or_b64 vcc, vcc, s[8:9]
	v_lshlrev_b32_e64 v50, v48, 1
	v_addc_co_u32_e32 v179, vcc, 0, v179, vcc
	s_cmp_lt_u32 s77, 13
	s_cbranch_scc1 .Lrk_done
	v_cmp_lt_u32_e64 s[10:11], 13, v48
	v_cmp_eq_f32_e64 s[8:9], v173, v176
	v_cmp_gt_f32_e32 vcc, v173, v176
	s_and_b64 s[8:9], s[8:9], s[10:11]
	s_or_b64 vcc, vcc, s[8:9]
	v_cmp_le_u32_e64 s[12:13], 13, v48
	v_addc_co_u32_e32 v178, vcc, 0, v178, vcc
	v_cmp_eq_f32_e64 s[8:9], v173, v177
	v_cmp_gt_f32_e32 vcc, v173, v177
	s_and_b64 s[8:9], s[8:9], s[12:13]
	s_or_b64 vcc, vcc, s[8:9]
	v_lshlrev_b32_e64 v50, v48, 1
	v_addc_co_u32_e32 v179, vcc, 0, v179, vcc
	s_cmp_lt_u32 s77, 14
	s_cbranch_scc1 .Lrk_done
	v_cmp_lt_u32_e64 s[10:11], 14, v48
	v_cmp_eq_f32_e64 s[8:9], v174, v176
	v_cmp_gt_f32_e32 vcc, v174, v176
	s_and_b64 s[8:9], s[8:9], s[10:11]
	s_or_b64 vcc, vcc, s[8:9]
	v_cmp_le_u32_e64 s[12:13], 14, v48
	v_addc_co_u32_e32 v178, vcc, 0, v178, vcc
	v_cmp_eq_f32_e64 s[8:9], v174, v177
	v_cmp_gt_f32_e32 vcc, v174, v177
	s_and_b64 s[8:9], s[8:9], s[12:13]
	s_or_b64 vcc, vcc, s[8:9]
	v_lshlrev_b32_e64 v50, v48, 1
	v_addc_co_u32_e32 v179, vcc, 0, v179, vcc
	s_cmp_lt_u32 s77, 15
	s_cbranch_scc1 .Lrk_done
	v_cmp_lt_u32_e64 s[10:11], 15, v48
	v_cmp_eq_f32_e64 s[8:9], v175, v176
	v_cmp_gt_f32_e32 vcc, v175, v176
	s_and_b64 s[8:9], s[8:9], s[10:11]
	s_or_b64 vcc, vcc, s[8:9]
	v_cmp_le_u32_e64 s[12:13], 15, v48
	v_addc_co_u32_e32 v178, vcc, 0, v178, vcc
	v_cmp_eq_f32_e64 s[8:9], v175, v177
	v_cmp_gt_f32_e32 vcc, v175, v177
	s_and_b64 s[8:9], s[8:9], s[12:13]
	s_or_b64 vcc, vcc, s[8:9]
	v_lshlrev_b32_e64 v50, v48, 1
	v_addc_co_u32_e32 v179, vcc, 0, v179, vcc
	s_waitcnt lgkmcnt(0)
	s_cmp_lt_u32 s77, 16
	s_cbranch_scc1 .Lrk_done
	v_cmp_lt_u32_e64 s[10:11], 16, v48
	v_cmp_eq_f32_e64 s[8:9], v142, v176
	v_cmp_gt_f32_e32 vcc, v142, v176
	s_and_b64 s[8:9], s[8:9], s[10:11]
	s_or_b64 vcc, vcc, s[8:9]
	v_cmp_le_u32_e64 s[12:13], 16, v48
	v_addc_co_u32_e32 v178, vcc, 0, v178, vcc
	v_cmp_eq_f32_e64 s[8:9], v142, v177
	v_cmp_gt_f32_e32 vcc, v142, v177
	s_and_b64 s[8:9], s[8:9], s[12:13]
	s_or_b64 vcc, vcc, s[8:9]
	v_lshlrev_b32_e64 v50, v48, 1
	v_addc_co_u32_e32 v179, vcc, 0, v179, vcc
	s_cmp_lt_u32 s77, 17
	s_cbranch_scc1 .Lrk_done
	v_cmp_lt_u32_e64 s[10:11], 17, v48
	v_cmp_eq_f32_e64 s[8:9], v143, v176
	v_cmp_gt_f32_e32 vcc, v143, v176
	s_and_b64 s[8:9], s[8:9], s[10:11]
	s_or_b64 vcc, vcc, s[8:9]
	v_cmp_le_u32_e64 s[12:13], 17, v48
	v_addc_co_u32_e32 v178, vcc, 0, v178, vcc
	v_cmp_eq_f32_e64 s[8:9], v143, v177
	v_cmp_gt_f32_e32 vcc, v143, v177
	s_and_b64 s[8:9], s[8:9], s[12:13]
	s_or_b64 vcc, vcc, s[8:9]
	v_lshlrev_b32_e64 v50, v48, 1
	v_addc_co_u32_e32 v179, vcc, 0, v179, vcc
	s_cmp_lt_u32 s77, 18
	s_cbranch_scc1 .Lrk_done
	v_cmp_lt_u32_e64 s[10:11], 18, v48
	v_cmp_eq_f32_e64 s[8:9], v144, v176
	v_cmp_gt_f32_e32 vcc, v144, v176
	s_and_b64 s[8:9], s[8:9], s[10:11]
	s_or_b64 vcc, vcc, s[8:9]
	v_cmp_le_u32_e64 s[12:13], 18, v48
	v_addc_co_u32_e32 v178, vcc, 0, v178, vcc
	v_cmp_eq_f32_e64 s[8:9], v144, v177
	v_cmp_gt_f32_e32 vcc, v144, v177
	s_and_b64 s[8:9], s[8:9], s[12:13]
	s_or_b64 vcc, vcc, s[8:9]
	v_lshlrev_b32_e64 v50, v48, 1
	v_addc_co_u32_e32 v179, vcc, 0, v179, vcc
	s_cmp_lt_u32 s77, 19
	s_cbranch_scc1 .Lrk_done
; DI void nsa_unit(const Params& p, lds8* lds, int bl, int g, int qb32) {
;     ...
;       if (s <= blk) { const float v = score[qq * 33 + s]; int rank = 0;
;         for (int s2 = 0; s2 <= blk; ++s2) { const float v2 = score[qq * 33 + s2]; rank += (v2 > v || (v2 == v && s2 < s)) ? 1 : 0; }
;         if (rank < 16) bits |= 1u << s; } }
	v_cmp_lt_u32_e64 s[10:11], 19, v48
	v_cmp_eq_f32_e64 s[8:9], v145, v176
	v_cmp_gt_f32_e32 vcc, v145, v176
	s_and_b64 s[8:9], s[8:9], s[10:11]
	s_or_b64 vcc, vcc, s[8:9]
	v_cmp_le_u32_e64 s[12:13], 19, v48
	v_addc_co_u32_e32 v178, vcc, 0, v178, vcc
	v_cmp_eq_f32_e64 s[8:9], v145, v177
	v_cmp_gt_f32_e32 vcc, v145, v177
	s_and_b64 s[8:9], s[8:9], s[12:13]
	s_or_b64 vcc, vcc, s[8:9]
	v_lshlrev_b32_e64 v50, v48, 1
	v_addc_co_u32_e32 v179, vcc, 0, v179, vcc
	s_cmp_lt_u32 s77, 20
	s_cbranch_scc1 .Lrk_done
	v_cmp_lt_u32_e64 s[10:11], 20, v48
	v_cmp_eq_f32_e64 s[8:9], v146, v176
	v_cmp_gt_f32_e32 vcc, v146, v176
	s_and_b64 s[8:9], s[8:9], s[10:11]
	s_or_b64 vcc, vcc, s[8:9]
	v_cmp_le_u32_e64 s[12:13], 20, v48
	v_addc_co_u32_e32 v178, vcc, 0, v178, vcc
	v_cmp_eq_f32_e64 s[8:9], v146, v177
	v_cmp_gt_f32_e32 vcc, v146, v177
	s_and_b64 s[8:9], s[8:9], s[12:13]
	s_or_b64 vcc, vcc, s[8:9]
	v_lshlrev_b32_e64 v50, v48, 1
	v_addc_co_u32_e32 v179, vcc, 0, v179, vcc
	s_cmp_lt_u32 s77, 21
	s_cbranch_scc1 .Lrk_done
	v_cmp_lt_u32_e64 s[10:11], 21, v48
	v_cmp_eq_f32_e64 s[8:9], v147, v176
	v_cmp_gt_f32_e32 vcc, v147, v176
	s_and_b64 s[8:9], s[8:9], s[10:11]
	s_or_b64 vcc, vcc, s[8:9]
	v_cmp_le_u32_e64 s[12:13], 21, v48
	v_addc_co_u32_e32 v178, vcc, 0, v178, vcc
	v_cmp_eq_f32_e64 s[8:9], v147, v177
	v_cmp_gt_f32_e32 vcc, v147, v177
	s_and_b64 s[8:9], s[8:9], s[12:13]
	s_or_b64 vcc, vcc, s[8:9]
	v_lshlrev_b32_e64 v50, v48, 1
	v_addc_co_u32_e32 v179, vcc, 0, v179, vcc
	s_cmp_lt_u32 s77, 22
	s_cbranch_scc1 .Lrk_done
	v_cmp_lt_u32_e64 s[10:11], 22, v48
	v_cmp_eq_f32_e64 s[8:9], v148, v176
	v_cmp_gt_f32_e32 vcc, v148, v176
	s_and_b64 s[8:9], s[8:9], s[10:11]
	s_or_b64 vcc, vcc, s[8:9]
	v_cmp_le_u32_e64 s[12:13], 22, v48
	v_addc_co_u32_e32 v178, vcc, 0, v178, vcc
	v_cmp_eq_f32_e64 s[8:9], v148, v177
	v_cmp_gt_f32_e32 vcc, v148, v177
	s_and_b64 s[8:9], s[8:9], s[12:13]
	s_or_b64 vcc, vcc, s[8:9]
	v_lshlrev_b32_e64 v50, v48, 1
	v_addc_co_u32_e32 v179, vcc, 0, v179, vcc
	s_cmp_lt_u32 s77, 23
	s_cbranch_scc1 .Lrk_done
	v_cmp_lt_u32_e64 s[10:11], 23, v48
	v_cmp_eq_f32_e64 s[8:9], v149, v176
	v_cmp_gt_f32_e32 vcc, v149, v176
	s_and_b64 s[8:9], s[8:9], s[10:11]
	s_or_b64 vcc, vcc, s[8:9]
	v_cmp_le_u32_e64 s[12:13], 23, v48
	v_addc_co_u32_e32 v178, vcc, 0, v178, vcc
	v_cmp_eq_f32_e64 s[8:9], v149, v177
	v_cmp_gt_f32_e32 vcc, v149, v177
	s_and_b64 s[8:9], s[8:9], s[12:13]
	s_or_b64 vcc, vcc, s[8:9]
	v_lshlrev_b32_e64 v50, v48, 1
	v_addc_co_u32_e32 v179, vcc, 0, v179, vcc
	s_cmp_lt_u32 s77, 24
	s_cbranch_scc1 .Lrk_done
	v_cmp_lt_u32_e64 s[10:11], 24, v48
	v_cmp_eq_f32_e64 s[8:9], v150, v176
	v_cmp_gt_f32_e32 vcc, v150, v176
	s_and_b64 s[8:9], s[8:9], s[10:11]
	s_or_b64 vcc, vcc, s[8:9]
	v_cmp_le_u32_e64 s[12:13], 24, v48
	v_addc_co_u32_e32 v178, vcc, 0, v178, vcc
	v_cmp_eq_f32_e64 s[8:9], v150, v177
	v_cmp_gt_f32_e32 vcc, v150, v177
	s_and_b64 s[8:9], s[8:9], s[12:13]
	s_or_b64 vcc, vcc, s[8:9]
	v_lshlrev_b32_e64 v50, v48, 1
	v_addc_co_u32_e32 v179, vcc, 0, v179, vcc
	s_cmp_lt_u32 s77, 25
	s_cbranch_scc1 .Lrk_done
	v_cmp_lt_u32_e64 s[10:11], 25, v48
	v_cmp_eq_f32_e64 s[8:9], v151, v176
	v_cmp_gt_f32_e32 vcc, v151, v176
	s_and_b64 s[8:9], s[8:9], s[10:11]
	s_or_b64 vcc, vcc, s[8:9]
	v_cmp_le_u32_e64 s[12:13], 25, v48
	v_addc_co_u32_e32 v178, vcc, 0, v178, vcc
	v_cmp_eq_f32_e64 s[8:9], v151, v177
	v_cmp_gt_f32_e32 vcc, v151, v177
	s_and_b64 s[8:9], s[8:9], s[12:13]
	s_or_b64 vcc, vcc, s[8:9]
	v_lshlrev_b32_e64 v50, v48, 1
	v_addc_co_u32_e32 v179, vcc, 0, v179, vcc
	s_cmp_lt_u32 s77, 26
	s_cbranch_scc1 .Lrk_done
	v_cmp_lt_u32_e64 s[10:11], 26, v48
	v_cmp_eq_f32_e64 s[8:9], v152, v176
	v_cmp_gt_f32_e32 vcc, v152, v176
	s_and_b64 s[8:9], s[8:9], s[10:11]
	s_or_b64 vcc, vcc, s[8:9]
	v_cmp_le_u32_e64 s[12:13], 26, v48
	v_addc_co_u32_e32 v178, vcc, 0, v178, vcc
	v_cmp_eq_f32_e64 s[8:9], v152, v177
	v_cmp_gt_f32_e32 vcc, v152, v177
	s_and_b64 s[8:9], s[8:9], s[12:13]
	s_or_b64 vcc, vcc, s[8:9]
	v_lshlrev_b32_e64 v50, v48, 1
	v_addc_co_u32_e32 v179, vcc, 0, v179, vcc
	s_cmp_lt_u32 s77, 27
	s_cbranch_scc1 .Lrk_done
	v_cmp_lt_u32_e64 s[10:11], 27, v48
	v_cmp_eq_f32_e64 s[8:9], v153, v176
	v_cmp_gt_f32_e32 vcc, v153, v176
	s_and_b64 s[8:9], s[8:9], s[10:11]
	s_or_b64 vcc, vcc, s[8:9]
	v_cmp_le_u32_e64 s[12:13], 27, v48
	v_addc_co_u32_e32 v178, vcc, 0, v178, vcc
	v_cmp_eq_f32_e64 s[8:9], v153, v177
	v_cmp_gt_f32_e32 vcc, v153, v177
	s_and_b64 s[8:9], s[8:9], s[12:13]
	s_or_b64 vcc, vcc, s[8:9]
	v_lshlrev_b32_e64 v50, v48, 1
	v_addc_co_u32_e32 v179, vcc, 0, v179, vcc
	s_cmp_lt_u32 s77, 28
	s_cbranch_scc1 .Lrk_done
	v_cmp_lt_u32_e64 s[10:11], 28, v48
	v_cmp_eq_f32_e64 s[8:9], v154, v176
	v_cmp_gt_f32_e32 vcc, v154, v176
	s_and_b64 s[8:9], s[8:9], s[10:11]
	s_or_b64 vcc, vcc, s[8:9]
	v_cmp_le_u32_e64 s[12:13], 28, v48
	v_addc_co_u32_e32 v178, vcc, 0, v178, vcc
	v_cmp_eq_f32_e64 s[8:9], v154, v177
	v_cmp_gt_f32_e32 vcc, v154, v177
	s_and_b64 s[8:9], s[8:9], s[12:13]
	s_or_b64 vcc, vcc, s[8:9]
	v_lshlrev_b32_e64 v50, v48, 1
	v_addc_co_u32_e32 v179, vcc, 0, v179, vcc
	s_cmp_lt_u32 s77, 29
	s_cbranch_scc1 .Lrk_done
	v_cmp_lt_u32_e64 s[10:11], 29, v48
	v_cmp_eq_f32_e64 s[8:9], v155, v176
	v_cmp_gt_f32_e32 vcc, v155, v176
	s_and_b64 s[8:9], s[8:9], s[10:11]
	s_or_b64 vcc, vcc, s[8:9]
	v_cmp_le_u32_e64 s[12:13], 29, v48
	v_addc_co_u32_e32 v178, vcc, 0, v178, vcc
	v_cmp_eq_f32_e64 s[8:9], v155, v177
	v_cmp_gt_f32_e32 vcc, v155, v177
	s_and_b64 s[8:9], s[8:9], s[12:13]
	s_or_b64 vcc, vcc, s[8:9]
	v_lshlrev_b32_e64 v50, v48, 1
	v_addc_co_u32_e32 v179, vcc, 0, v179, vcc
	s_cmp_lt_u32 s77, 30
	s_cbranch_scc1 .Lrk_done
	v_cmp_lt_u32_e64 s[10:11], 30, v48
	v_cmp_eq_f32_e64 s[8:9], v156, v176
	v_cmp_gt_f32_e32 vcc, v156, v176
	s_and_b64 s[8:9], s[8:9], s[10:11]
	s_or_b64 vcc, vcc, s[8:9]
	v_cmp_le_u32_e64 s[12:13], 30, v48
	v_addc_co_u32_e32 v178, vcc, 0, v178, vcc
	v_cmp_eq_f32_e64 s[8:9], v156, v177
	v_cmp_gt_f32_e32 vcc, v156, v177
	s_and_b64 s[8:9], s[8:9], s[12:13]
	s_or_b64 vcc, vcc, s[8:9]
	v_lshlrev_b32_e64 v50, v48, 1
	v_addc_co_u32_e32 v179, vcc, 0, v179, vcc
	s_cmp_lt_u32 s77, 31
	s_cbranch_scc1 .Lrk_done
	v_cmp_lt_u32_e64 s[10:11], 31, v48
	v_cmp_eq_f32_e64 s[8:9], v157, v176
	v_cmp_gt_f32_e32 vcc, v157, v176
	s_and_b64 s[8:9], s[8:9], s[10:11]
	s_or_b64 vcc, vcc, s[8:9]
	v_cmp_le_u32_e64 s[12:13], 31, v48
	v_addc_co_u32_e32 v178, vcc, 0, v178, vcc
	v_cmp_eq_f32_e64 s[8:9], v157, v177
	v_cmp_gt_f32_e32 vcc, v157, v177
	s_and_b64 s[8:9], s[8:9], s[12:13]
	s_or_b64 vcc, vcc, s[8:9]
	v_lshlrev_b32_e64 v50, v48, 1
	v_addc_co_u32_e32 v179, vcc, 0, v179, vcc
; DI void nsa_unit(const Params& p, lds8* lds, int bl, int g, int qb32) {
;     ...
;   { const int qq = tid >> 4, sb2 = (tid & 15) * 2; unsigned bits = 0u;
; #pragma unroll
;     for (int e = 0; e < 2; ++e) { const int s = sb2 + e;
;       if (s <= blk) { const float v = score[qq * 33 + s]; int rank = 0;
;         for (int s2 = 0; s2 <= blk; ++s2) { const float v2 = score[qq * 33 + s2]; rank += (v2 > v || (v2 == v && s2 < s)) ? 1 : 0; }
;         if (rank < 16) bits |= 1u << s; } }
;     bits |= __shfl_xor(bits, 1); bits |= __shfl_xor(bits, 2); bits |= __shfl_xor(bits, 4); bits |= __shfl_xor(bits, 8);
;     if ((tid & 15) == 0) { maskl[qq] = bits; atomicOr((unsigned*)umaskl, bits); } }
.Lrk_done:
	s_waitcnt lgkmcnt(0)
	v_cmp_ge_u32_e32 vcc, s77, v48
	v_cmp_gt_u32_e64 s[8:9], 16, v178
	s_and_b64 vcc, vcc, s[8:9]
	v_lshlrev_b32_e64 v50, v48, 1
	v_cndmask_b32_e32 v60, 0, v50, vcc
	v_cmp_gt_u32_e32 vcc, s77, v48
	v_cmp_gt_u32_e64 s[8:9], 16, v179
	s_and_b64 vcc, vcc, s[8:9]
	v_lshlrev_b32_e64 v50, v48, 2
	s_nop 0
	v_cndmask_b32_e32 v50, 0, v50, vcc
	v_or_b32_e32 v60, v50, v60
	v_xor_b32_e32 v48, 1, v202
	v_cmp_lt_i32_e32 vcc, v48, v53
	v_xor_b32_e32 v49, 2, v202
	s_nop 0
	v_cndmask_b32_e32 v48, v202, v48, vcc
	v_lshlrev_b32_e32 v48, 2, v48
	ds_bpermute_b32 v48, v48, v60
	v_cmp_lt_i32_e32 vcc, v49, v53
	s_waitcnt lgkmcnt(0)
	v_or_b32_e32 v48, v48, v60
	v_cndmask_b32_e32 v49, v202, v49, vcc
	v_lshlrev_b32_e32 v49, 2, v49
	ds_bpermute_b32 v49, v49, v48
	s_waitcnt lgkmcnt(0)
	v_or_b32_e32 v48, v48, v49
	v_xor_b32_e32 v49, 4, v202
	v_cmp_lt_i32_e32 vcc, v49, v53
	s_nop 1
	v_cndmask_b32_e32 v49, v202, v49, vcc
	v_lshlrev_b32_e32 v49, 2, v49
	ds_bpermute_b32 v49, v49, v48
	s_waitcnt lgkmcnt(0)
	v_or_b32_e32 v48, v48, v49
	v_xor_b32_e32 v49, 8, v202
	v_cmp_lt_i32_e32 vcc, v49, v53
	s_nop 1
	v_cndmask_b32_e32 v49, v202, v49, vcc
	v_lshlrev_b32_e32 v49, 2, v49
	ds_bpermute_b32 v49, v49, v48
	v_cmp_eq_u32_e32 vcc, 0, v56
	s_and_saveexec_b64 s[8:9], vcc
	s_cbranch_execz .LBB0_929
	s_waitcnt lgkmcnt(0)
	v_or_b32_e32 v48, v48, v49
	v_lshl_add_u32 v49, v55, 2, 0
	s_mov_b64 s[10:11], exec
	v_add_u32_e32 v49, 0x16c80, v49
	s_mov_b32 s6, 0
	ds_write_b32 v49, v48
